# ssdc item epilogue and merge_a gate epilogue: hoisted loads ahead of the store ladders (counted waits)
# speedup vs baseline: 1.0230x; 1.0008x over previous
; __device__ __forceinline__ unsigned pk2(float lo, float hi) { const f32x2 v = {lo, hi}; const bf16x2_t b = __builtin_convertvector(v, bf16x2_t); return __builtin_bit_cast(unsigned, b); }
; #define INF(i) ((const float*)in_ptr(i))
; __device__ __forceinline__ void ph_ssdc(LAS unsigned char* lds) {
;     ...
; #pragma unroll
;         for (int li = 0; li < 2; ++li) { const int lb = li == 0 ? (wl ? 1 : 0) : (wl ? 2 : 3); const int l = lb * 32 + r32;
;             const float rs = rsqrtf((rowp[l] + rowp[128 + l] + rowp[256 + l] + rowp[384 + l]) * (1.f / 256.f) + EPS);
;             bf16_t* op = (bf16_t*)(ws + WS_SSM) + (unsigned)((trow0 + l) * 2048 + g * 256 + h * 64 + 4 * hf); const float* gp = INF(18) + g * 256 + h * 64 + 4 * hf;
; #pragma unroll
;             for (int pb = 0; pb < 2; ++pb)
; #pragma unroll
;                 for (int rg = 0; rg < 4; ++rg) { const f32x4 gs = *(const f32x4*)(gp + pb * 32 + 8 * rg);
;                     u32x2 w; w.x = pk2(yacc[li][pb][4 * rg] * rs * gs[0], yacc[li][pb][4 * rg + 1] * rs * gs[1]); w.y = pk2(yacc[li][pb][4 * rg + 2] * rs * gs[2], yacc[li][pb][4 * rg + 3] * rs * gs[3]);
;                     *(u32x2*)(op + pb * 32 + 8 * rg) = w; } }
.LBB0_956:
	s_or_b64 exec, exec, s[4:5]
	s_movk_i32 s2, 0x90
	s_waitcnt lgkmcnt(0)
	s_barrier
	ds_read2st64_b32 v[72:73], v200 offset1:2
	ds_read2st64_b32 v[74:75], v200 offset0:4 offset1:6
	s_ashr_i32 s5, s2, 31
	s_add_u32 s4, s0, s2
	s_addc_u32 s5, s1, s5
	s_load_dwordx2 s[4:5], s[4:5], 0x0
	s_lshl_b32 s2, s19, 2
	s_waitcnt lgkmcnt(0)
	v_mov_b32_e32 v81, v72
	v_mov_b32_e32 v83, v74
	v_lshl_add_u64 v[66:67], v[66:67], 1, s[90:91]
	s_add_u32 s4, s4, s2
	s_addc_u32 s5, s5, 0
	s_add_u32 s4, s4, s92
	s_addc_u32 s5, s5, s93
	global_load_dwordx4 v[144:147], v213, s[4:5]
	global_load_dwordx4 v[148:151], v213, s[4:5] offset:32
	global_load_dwordx4 v[152:155], v213, s[4:5] offset:64
	global_load_dwordx4 v[156:159], v213, s[4:5] offset:96
	global_load_dwordx4 v[160:163], v213, s[4:5] offset:128
	global_load_dwordx4 v[164:167], v213, s[4:5] offset:160
	global_load_dwordx4 v[168:171], v213, s[4:5] offset:192
	global_load_dwordx4 v[112:115], v213, s[4:5] offset:224
	ds_read2st64_b32 v[76:77], v201 offset1:2
	ds_read2st64_b32 v[78:79], v201 offset0:4 offset1:6
	s_waitcnt lgkmcnt(1)
	v_mov_b32_e32 v80, v76
	v_mov_b32_e32 v72, v77
	s_waitcnt lgkmcnt(0)
	v_mov_b32_e32 v82, v78
	v_pk_add_f32 v[72:73], v[80:81], v[72:73]
	v_mov_b32_e32 v74, v79
	v_pk_add_f32 v[72:73], v[72:73], v[82:83]
	s_nop 0
	v_pk_add_f32 v[72:73], v[72:73], v[74:75]
	s_nop 0
	v_pk_fma_f32 v[72:73], v[72:73], s[76:77], v[220:221] op_sel_hi:[1,0,0]
	s_nop 0
	v_mul_f32_e32 v74, 0x4b800000, v73
	v_cmp_gt_f32_e32 vcc, s51, v73
	s_nop 1
	v_cndmask_b32_e32 v73, v73, v74, vcc
	v_rsq_f32_e32 v73, v73
	s_nop 0
	v_mul_f32_e32 v74, 0x45800000, v73
	v_cndmask_b32_e32 v74, v73, v74, vcc
	v_pk_mul_f32 v[34:35], v[34:35], v[74:75] op_sel_hi:[1,0]
	v_pk_mul_f32 v[36:37], v[36:37], v[74:75] op_sel_hi:[1,0]
	v_pk_mul_f32 v[38:39], v[38:39], v[74:75] op_sel_hi:[1,0]
	v_pk_mul_f32 v[40:41], v[40:41], v[74:75] op_sel_hi:[1,0]
	v_pk_mul_f32 v[2:3], v[2:3], v[74:75] op_sel_hi:[1,0]
	v_pk_mul_f32 v[4:5], v[4:5], v[74:75] op_sel_hi:[1,0]
	v_pk_mul_f32 v[6:7], v[6:7], v[74:75] op_sel_hi:[1,0]
	v_pk_mul_f32 v[8:9], v[8:9], v[74:75] op_sel_hi:[1,0]
	v_cmp_gt_f32_e32 vcc, s51, v72
	s_waitcnt vmcnt(0)
	v_pk_mul_f32 v[34:35], v[144:145], v[34:35]
	v_pk_mul_f32 v[36:37], v[146:147], v[36:37]
	v_cvt_pk_bf16_f32 v34, v34, v35
	v_cvt_pk_bf16_f32 v35, v36, v37
	global_store_dwordx2 v[66:67], v[34:35], off
	v_pk_mul_f32 v[34:35], v[148:149], v[38:39]
	v_pk_mul_f32 v[36:37], v[150:151], v[40:41]
	v_cvt_pk_bf16_f32 v34, v34, v35
	v_cvt_pk_bf16_f32 v35, v36, v37
	global_store_dwordx2 v[66:67], v[34:35], off offset:16
	v_pk_mul_f32 v[38:39], v[42:43], v[74:75] op_sel_hi:[1,0]
	v_pk_mul_f32 v[40:41], v[44:45], v[74:75] op_sel_hi:[1,0]
	v_pk_mul_f32 v[34:35], v[152:153], v[38:39]
	v_pk_mul_f32 v[36:37], v[154:155], v[40:41]
	v_cvt_pk_bf16_f32 v34, v34, v35
	v_cvt_pk_bf16_f32 v35, v36, v37
	global_store_dwordx2 v[66:67], v[34:35], off offset:32
	v_pk_mul_f32 v[38:39], v[46:47], v[74:75] op_sel_hi:[1,0]
	v_pk_mul_f32 v[40:41], v[48:49], v[74:75] op_sel_hi:[1,0]
	v_pk_mul_f32 v[34:35], v[38:39], v[156:157]
	v_pk_mul_f32 v[36:37], v[40:41], v[158:159]
	v_cvt_pk_bf16_f32 v34, v34, v35
	v_cvt_pk_bf16_f32 v35, v36, v37
	global_store_dwordx2 v[66:67], v[34:35], off offset:48
	v_pk_mul_f32 v[2:3], v[2:3], v[160:161]
	v_pk_mul_f32 v[4:5], v[4:5], v[162:163]
	v_cvt_pk_bf16_f32 v2, v2, v3
	v_cvt_pk_bf16_f32 v3, v4, v5
	global_store_dwordx2 v[66:67], v[2:3], off offset:64
	v_pk_mul_f32 v[2:3], v[6:7], v[164:165]
	v_pk_mul_f32 v[4:5], v[8:9], v[166:167]
	v_cvt_pk_bf16_f32 v2, v2, v3
	v_cvt_pk_bf16_f32 v3, v4, v5
	global_store_dwordx2 v[66:67], v[2:3], off offset:80
	v_pk_mul_f32 v[6:7], v[10:11], v[74:75] op_sel_hi:[1,0]
	v_pk_mul_f32 v[8:9], v[12:13], v[74:75] op_sel_hi:[1,0]
	v_pk_mul_f32 v[2:3], v[6:7], v[168:169]
	v_pk_mul_f32 v[4:5], v[8:9], v[170:171]
	v_cvt_pk_bf16_f32 v2, v2, v3
	v_cvt_pk_bf16_f32 v3, v4, v5
	global_store_dwordx2 v[66:67], v[2:3], off offset:96
	v_pk_mul_f32 v[6:7], v[14:15], v[74:75] op_sel_hi:[1,0]
	v_pk_mul_f32 v[8:9], v[16:17], v[74:75] op_sel_hi:[1,0]
	s_movk_i32 s4, 0x90
	v_pk_mul_f32 v[2:3], v[6:7], v[112:113]
	v_pk_mul_f32 v[4:5], v[8:9], v[114:115]
	v_cvt_pk_bf16_f32 v2, v2, v3
	v_cvt_pk_bf16_f32 v3, v4, v5
	global_store_dwordx2 v[66:67], v[2:3], off offset:112
	s_ashr_i32 s5, s4, 31
	s_add_u32 s4, s0, s4
	s_addc_u32 s5, s1, s5
	s_load_dwordx2 s[4:5], s[4:5], 0x0
	v_mul_f32_e32 v6, 0x4b800000, v72
	v_cndmask_b32_e32 v6, v72, v6, vcc
	v_rsq_f32_e32 v8, v6
	v_lshl_add_u64 v[6:7], v[0:1], 1, s[90:91]
	s_waitcnt lgkmcnt(0)
; __device__ __forceinline__ unsigned pk2(float lo, float hi) { const f32x2 v = {lo, hi}; const bf16x2_t b = __builtin_convertvector(v, bf16x2_t); return __builtin_bit_cast(unsigned, b); }
; #define INF(i) ((const float*)in_ptr(i))
; __device__ __forceinline__ void ph_ssdc(LAS unsigned char* lds) {
;     ...
; #pragma unroll
;         for (int li = 0; li < 2; ++li) { const int lb = li == 0 ? (wl ? 1 : 0) : (wl ? 2 : 3); const int l = lb * 32 + r32;
;             const float rs = rsqrtf((rowp[l] + rowp[128 + l] + rowp[256 + l] + rowp[384 + l]) * (1.f / 256.f) + EPS);
;             bf16_t* op = (bf16_t*)(ws + WS_SSM) + (unsigned)((trow0 + l) * 2048 + g * 256 + h * 64 + 4 * hf); const float* gp = INF(18) + g * 256 + h * 64 + 4 * hf;
; #pragma unroll
;             for (int pb = 0; pb < 2; ++pb)
; #pragma unroll
;                 for (int rg = 0; rg < 4; ++rg) { const f32x4 gs = *(const f32x4*)(gp + pb * 32 + 8 * rg);
;                     u32x2 w; w.x = pk2(yacc[li][pb][4 * rg] * rs * gs[0], yacc[li][pb][4 * rg + 1] * rs * gs[1]); w.y = pk2(yacc[li][pb][4 * rg + 2] * rs * gs[2], yacc[li][pb][4 * rg + 3] * rs * gs[3]);
;                     *(u32x2*)(op + pb * 32 + 8 * rg) = w; } }
	s_add_u32 s2, s4, s2
	s_addc_u32 s5, s5, 0
	s_add_u32 s4, s2, s92
	s_addc_u32 s5, s5, s93
	v_mul_f32_e32 v0, 0x45800000, v8
	v_cndmask_b32_e32 v0, v8, v0, vcc
	v_pk_mul_f32 v[8:9], v[50:51], v[0:1] op_sel_hi:[1,0]
	v_pk_mul_f32 v[10:11], v[52:53], v[0:1] op_sel_hi:[1,0]
	s_add_i32 s42, s42, s6
	s_cmpk_lt_i32 s42, 0x400
	v_pk_mul_f32 v[2:3], v[144:145], v[8:9]
	v_pk_mul_f32 v[4:5], v[146:147], v[10:11]
	v_cvt_pk_bf16_f32 v2, v2, v3
	v_cvt_pk_bf16_f32 v3, v4, v5
	global_store_dwordx2 v[6:7], v[2:3], off
	v_pk_mul_f32 v[8:9], v[54:55], v[0:1] op_sel_hi:[1,0]
	v_pk_mul_f32 v[10:11], v[56:57], v[0:1] op_sel_hi:[1,0]
	v_pk_mul_f32 v[2:3], v[148:149], v[8:9]
	v_pk_mul_f32 v[4:5], v[150:151], v[10:11]
	v_cvt_pk_bf16_f32 v2, v2, v3
	v_cvt_pk_bf16_f32 v3, v4, v5
	global_store_dwordx2 v[6:7], v[2:3], off offset:16
	v_pk_mul_f32 v[8:9], v[58:59], v[0:1] op_sel_hi:[1,0]
	v_pk_mul_f32 v[10:11], v[60:61], v[0:1] op_sel_hi:[1,0]
	v_pk_mul_f32 v[2:3], v[152:153], v[8:9]
	v_pk_mul_f32 v[4:5], v[154:155], v[10:11]
	v_cvt_pk_bf16_f32 v2, v2, v3
	v_cvt_pk_bf16_f32 v3, v4, v5
	global_store_dwordx2 v[6:7], v[2:3], off offset:32
	v_pk_mul_f32 v[8:9], v[62:63], v[0:1] op_sel_hi:[1,0]
	v_pk_mul_f32 v[10:11], v[64:65], v[0:1] op_sel_hi:[1,0]
	v_pk_mul_f32 v[2:3], v[8:9], v[156:157]
	v_pk_mul_f32 v[4:5], v[10:11], v[158:159]
	v_cvt_pk_bf16_f32 v2, v2, v3
	v_cvt_pk_bf16_f32 v3, v4, v5
	global_store_dwordx2 v[6:7], v[2:3], off offset:48
	v_pk_mul_f32 v[8:9], v[18:19], v[0:1] op_sel_hi:[1,0]
	v_pk_mul_f32 v[10:11], v[20:21], v[0:1] op_sel_hi:[1,0]
	v_pk_mul_f32 v[2:3], v[8:9], v[160:161]
	v_pk_mul_f32 v[4:5], v[10:11], v[162:163]
	v_cvt_pk_bf16_f32 v2, v2, v3
	v_cvt_pk_bf16_f32 v3, v4, v5
	global_store_dwordx2 v[6:7], v[2:3], off offset:64
	v_pk_mul_f32 v[8:9], v[22:23], v[0:1] op_sel_hi:[1,0]
	v_pk_mul_f32 v[10:11], v[24:25], v[0:1] op_sel_hi:[1,0]
	v_pk_mul_f32 v[2:3], v[8:9], v[164:165]
	v_pk_mul_f32 v[4:5], v[10:11], v[166:167]
	v_cvt_pk_bf16_f32 v2, v2, v3
	v_cvt_pk_bf16_f32 v3, v4, v5
	global_store_dwordx2 v[6:7], v[2:3], off offset:80
	v_pk_mul_f32 v[8:9], v[26:27], v[0:1] op_sel_hi:[1,0]
	v_pk_mul_f32 v[10:11], v[28:29], v[0:1] op_sel_hi:[1,0]
	v_pk_mul_f32 v[2:3], v[8:9], v[168:169]
	v_pk_mul_f32 v[4:5], v[10:11], v[170:171]
	v_cvt_pk_bf16_f32 v2, v2, v3
	v_cvt_pk_bf16_f32 v3, v4, v5
	global_store_dwordx2 v[6:7], v[2:3], off offset:96
	v_pk_mul_f32 v[8:9], v[30:31], v[0:1] op_sel_hi:[1,0]
	v_pk_mul_f32 v[10:11], v[32:33], v[0:1] op_sel_hi:[1,0]
	v_pk_mul_f32 v[2:3], v[8:9], v[112:113]
	v_pk_mul_f32 v[4:5], v[10:11], v[114:115]
	v_cvt_pk_bf16_f32 v2, v2, v3
	v_cvt_pk_bf16_f32 v3, v4, v5
	global_store_dwordx2 v[6:7], v[2:3], off offset:112
	s_cbranch_scc0 .LBB0_969

; __device__ __forceinline__ void st8(bf16_t* p, f32x4 a, f32x4 b) { u32x4 w; w.x = pk2(a[0], a[1]); w.y = pk2(a[2], a[3]); w.z = pk2(b[0], b[1]); w.w = pk2(b[2], b[3]); *(u32x4*)p = w; }
; __device__ __forceinline__ void ld8(const bf16_t* p, f32x4& a, f32x4& b) { const u32x4 w = *(const u32x4*)p; a[0] = bflo(w.x); a[1] = bfhi(w.x); a[2] = bflo(w.y); a[3] = bfhi(w.y); b[0] = bflo(w.z); b[1] = bfhi(w.z); b[2] = bflo(w.w); b[3] = bfhi(w.w); }
;     __device__ __forceinline__ void operator()(ACC_T, const pg8::Unit& u, int wr, int wc, int fr, int fq) const {
;         const int row0 = u.pm * 256 + wr * 64 + fr, col0 = u.pn * 256 + wc * 32 + 8 * fq;
; #pragma unroll
;         for (int ai = 0; ai < 2; ++ai)
; #pragma unroll
;             for (int m = 0; m < 4; ++m) { const int row = row0 + ai * 128 + m * 16;
; #pragma unroll
;                 for (int bj = 0; bj < 2; ++bj) { const unsigned off = (unsigned)row * 1024u + col0 + bj * 128; f32x4 g0, g1; ld8(G + off, g0, g1);
;                     f32x4 v0 = acc[ai][bj][m][0] * g0, v1 = acc[ai][bj][m][1] * g1;
;                     if (MODE == 1) { f32x4 p0, p1; ld8(P + off, p0, p1); v0 += p0; v1 += p1; }
;                     st8(O + off, v0, v1); }
;                 asm volatile("" ::: "memory"); }
;     }
.LBB0_1041:
	v_mov_b32_e32 v0, v142
	v_mov_b32_e32 v146, v143
	s_lshl_b32 s2, s84, 8
	s_add_i32 s2, s2, s45
	s_lshl_b32 s8, s68, 8
	v_lshlrev_b32_e32 v146, 3, v146
	v_add_lshl_u32 v0, s2, v0, 10
	s_or_b32 s2, s8, s60
	v_add3_u32 v0, s2, v146, v0
	v_lshlrev_b64 v[150:151], 1, v[0:1]
	v_mov_b32_e32 v156, v0
	v_mov_b32_e32 v157, v1
	v_lshlrev_b64 v[156:157], 1, v[156:157]
	v_lshl_add_u64 v[156:157], s[40:41], 0, v[156:157]
	global_load_dwordx4 v[156:159], v[156:157], off
	v_add_u32_e32 v160, 0x80, v0
	v_mov_b32_e32 v161, v1
	v_lshlrev_b64 v[160:161], 1, v[160:161]
	v_lshl_add_u64 v[160:161], s[40:41], 0, v[160:161]
	global_load_dwordx4 v[160:163], v[160:161], off
	v_add_u32_e32 v164, 0x4000, v0
	v_mov_b32_e32 v165, v1
	v_lshlrev_b64 v[164:165], 1, v[164:165]
	v_lshl_add_u64 v[164:165], s[40:41], 0, v[164:165]
	global_load_dwordx4 v[164:167], v[164:165], off
	v_add_u32_e32 v168, 0x4080, v0
	v_mov_b32_e32 v169, v1
	v_lshlrev_b64 v[168:169], 1, v[168:169]
	v_lshl_add_u64 v[168:169], s[40:41], 0, v[168:169]
	global_load_dwordx4 v[168:171], v[168:169], off
	v_add_u32_e32 v172, 0x8000, v0
	v_mov_b32_e32 v173, v1
	v_lshlrev_b64 v[172:173], 1, v[172:173]
	v_lshl_add_u64 v[172:173], s[40:41], 0, v[172:173]
	global_load_dwordx4 v[172:175], v[172:173], off
	v_add_u32_e32 v176, 0x8080, v0
	v_mov_b32_e32 v177, v1
	v_lshlrev_b64 v[176:177], 1, v[176:177]
	v_lshl_add_u64 v[176:177], s[40:41], 0, v[176:177]
	global_load_dwordx4 v[176:179], v[176:177], off
	v_add_u32_e32 v180, 0xc000, v0
	v_mov_b32_e32 v181, v1
	v_lshlrev_b64 v[180:181], 1, v[180:181]
	v_lshl_add_u64 v[180:181], s[40:41], 0, v[180:181]
	global_load_dwordx4 v[180:183], v[180:181], off
	v_add_u32_e32 v184, 0xc080, v0
	v_mov_b32_e32 v185, v1
	v_lshlrev_b64 v[184:185], 1, v[184:185]
	v_lshl_add_u64 v[184:185], s[40:41], 0, v[184:185]
	global_load_dwordx4 v[184:187], v[184:185], off
	v_add_u32_e32 v188, 0x20000, v0
	v_mov_b32_e32 v189, v1
	v_lshlrev_b64 v[188:189], 1, v[188:189]
	v_lshl_add_u64 v[188:189], s[40:41], 0, v[188:189]
	global_load_dwordx4 v[188:191], v[188:189], off
	v_add_u32_e32 v192, 0x20080, v0
	v_mov_b32_e32 v193, v1
	v_lshlrev_b64 v[192:193], 1, v[192:193]
	v_lshl_add_u64 v[192:193], s[40:41], 0, v[192:193]
	global_load_dwordx4 v[192:195], v[192:193], off
	v_add_u32_e32 v196, 0x24000, v0
	v_mov_b32_e32 v197, v1
	v_lshlrev_b64 v[196:197], 1, v[196:197]
	v_lshl_add_u64 v[196:197], s[40:41], 0, v[196:197]
	global_load_dwordx4 v[196:199], v[196:197], off
	v_add_u32_e32 v200, 0x24080, v0
	v_mov_b32_e32 v201, v1
	v_lshlrev_b64 v[200:201], 1, v[200:201]
	v_lshl_add_u64 v[200:201], s[40:41], 0, v[200:201]
	global_load_dwordx4 v[200:203], v[200:201], off
	v_add_u32_e32 v204, 0x28000, v0
	v_mov_b32_e32 v205, v1
	v_lshlrev_b64 v[204:205], 1, v[204:205]
	v_lshl_add_u64 v[204:205], s[40:41], 0, v[204:205]
	global_load_dwordx4 v[204:207], v[204:205], off
	v_add_u32_e32 v208, 0x28080, v0
	v_mov_b32_e32 v209, v1
	v_lshlrev_b64 v[208:209], 1, v[208:209]
	v_lshl_add_u64 v[208:209], s[40:41], 0, v[208:209]
	global_load_dwordx4 v[208:211], v[208:209], off
	v_add_u32_e32 v212, 0x2c000, v0
	v_mov_b32_e32 v213, v1
	v_lshlrev_b64 v[212:213], 1, v[212:213]
	v_lshl_add_u64 v[212:213], s[40:41], 0, v[212:213]
	global_load_dwordx4 v[212:215], v[212:213], off
	v_add_u32_e32 v216, 0x2c080, v0
	v_mov_b32_e32 v217, v1
	v_lshlrev_b64 v[216:217], 1, v[216:217]
	v_lshl_add_u64 v[216:217], s[40:41], 0, v[216:217]
	global_load_dwordx4 v[216:219], v[216:217], off
	s_waitcnt vmcnt(15)
	v_lshlrev_b32_e32 v152, 16, v156
	v_and_b32_e32 v153, 0xffff0000, v156
	v_lshlrev_b32_e32 v146, 16, v157
	v_and_b32_e32 v147, 0xffff0000, v157
	v_lshlrev_b32_e32 v154, 16, v158
	v_and_b32_e32 v155, 0xffff0000, v158
	v_lshlrev_b32_e32 v148, 16, v159
	v_and_b32_e32 v149, 0xffff0000, v159
	v_pk_mul_f32 v[128:129], v[128:129], v[146:147]
	v_pk_mul_f32 v[126:127], v[126:127], v[152:153]
	v_pk_mul_f32 v[146:147], v[124:125], v[148:149]
	v_pk_mul_f32 v[124:125], v[122:123], v[154:155]
	v_lshl_add_u64 v[148:149], s[6:7], 0, v[150:151]
	v_cvt_pk_bf16_f32 v122, v126, v127
	v_cvt_pk_bf16_f32 v123, v128, v129
	v_cvt_pk_bf16_f32 v124, v124, v125
	v_cvt_pk_bf16_f32 v125, v146, v147
	global_store_dwordx4 v[148:149], v[122:125], off sc1
	s_nop 1
	v_add_u32_e32 v122, 0x80, v0
	v_mov_b32_e32 v123, v1
	v_lshlrev_b64 v[126:127], 1, v[122:123]
	s_waitcnt vmcnt(15)
	v_lshlrev_b32_e32 v128, 16, v160
	v_and_b32_e32 v129, 0xffff0000, v160
	v_lshlrev_b32_e32 v122, 16, v161
	v_and_b32_e32 v123, 0xffff0000, v161
	v_lshlrev_b32_e32 v146, 16, v162
	v_and_b32_e32 v147, 0xffff0000, v162
	v_lshlrev_b32_e32 v124, 16, v163
	v_and_b32_e32 v125, 0xffff0000, v163
	v_pk_mul_f32 v[120:121], v[120:121], v[122:123]
	v_pk_mul_f32 v[118:119], v[118:119], v[128:129]
	v_pk_mul_f32 v[122:123], v[116:117], v[124:125]
	v_pk_mul_f32 v[116:117], v[114:115], v[146:147]
	v_lshl_add_u64 v[124:125], s[6:7], 0, v[126:127]
	v_cvt_pk_bf16_f32 v114, v118, v119
	v_cvt_pk_bf16_f32 v115, v120, v121
	v_cvt_pk_bf16_f32 v116, v116, v117
	v_cvt_pk_bf16_f32 v117, v122, v123
	global_store_dwordx4 v[124:125], v[114:117], off sc1
	s_nop 1
	v_add_u32_e32 v114, 0x4000, v0
	v_mov_b32_e32 v115, v1
	v_lshlrev_b64 v[118:119], 1, v[114:115]
	s_waitcnt vmcnt(15)
	v_lshlrev_b32_e32 v120, 16, v164
	v_and_b32_e32 v121, 0xffff0000, v164
	v_lshlrev_b32_e32 v114, 16, v165
	v_and_b32_e32 v115, 0xffff0000, v165
	v_lshlrev_b32_e32 v122, 16, v166
	v_and_b32_e32 v123, 0xffff0000, v166
	v_lshlrev_b32_e32 v116, 16, v167
	v_and_b32_e32 v117, 0xffff0000, v167
	v_pk_mul_f32 v[112:113], v[112:113], v[114:115]
	v_pk_mul_f32 v[110:111], v[110:111], v[120:121]
	v_pk_mul_f32 v[114:115], v[108:109], v[116:117]
	v_pk_mul_f32 v[108:109], v[106:107], v[122:123]
	v_lshl_add_u64 v[116:117], s[6:7], 0, v[118:119]
	v_cvt_pk_bf16_f32 v106, v110, v111
	v_cvt_pk_bf16_f32 v107, v112, v113
	v_cvt_pk_bf16_f32 v108, v108, v109
	v_cvt_pk_bf16_f32 v109, v114, v115
	global_store_dwordx4 v[116:117], v[106:109], off sc1
	s_nop 1
	v_add_u32_e32 v106, 0x4080, v0
	v_mov_b32_e32 v107, v1
	v_lshlrev_b64 v[110:111], 1, v[106:107]
	s_waitcnt vmcnt(15)
; __device__ __forceinline__ void st8(bf16_t* p, f32x4 a, f32x4 b) { u32x4 w; w.x = pk2(a[0], a[1]); w.y = pk2(a[2], a[3]); w.z = pk2(b[0], b[1]); w.w = pk2(b[2], b[3]); *(u32x4*)p = w; }
; __device__ __forceinline__ void ld8(const bf16_t* p, f32x4& a, f32x4& b) { const u32x4 w = *(const u32x4*)p; a[0] = bflo(w.x); a[1] = bfhi(w.x); a[2] = bflo(w.y); a[3] = bfhi(w.y); b[0] = bflo(w.z); b[1] = bfhi(w.z); b[2] = bflo(w.w); b[3] = bfhi(w.w); }
;     __device__ __forceinline__ void operator()(ACC_T, const pg8::Unit& u, int wr, int wc, int fr, int fq) const {
;         const int row0 = u.pm * 256 + wr * 64 + fr, col0 = u.pn * 256 + wc * 32 + 8 * fq;
; #pragma unroll
;         for (int ai = 0; ai < 2; ++ai)
; #pragma unroll
;             for (int m = 0; m < 4; ++m) { const int row = row0 + ai * 128 + m * 16;
; #pragma unroll
;                 for (int bj = 0; bj < 2; ++bj) { const unsigned off = (unsigned)row * 1024u + col0 + bj * 128; f32x4 g0, g1; ld8(G + off, g0, g1);
;                     f32x4 v0 = acc[ai][bj][m][0] * g0, v1 = acc[ai][bj][m][1] * g1;
;                     if (MODE == 1) { f32x4 p0, p1; ld8(P + off, p0, p1); v0 += p0; v1 += p1; }
;                     st8(O + off, v0, v1); }
;                 asm volatile("" ::: "memory"); }
;     }
	v_lshlrev_b32_e32 v112, 16, v168
	v_and_b32_e32 v113, 0xffff0000, v168
	v_lshlrev_b32_e32 v106, 16, v169
	v_and_b32_e32 v107, 0xffff0000, v169
	v_lshlrev_b32_e32 v114, 16, v170
	v_and_b32_e32 v115, 0xffff0000, v170
	v_lshlrev_b32_e32 v108, 16, v171
	v_and_b32_e32 v109, 0xffff0000, v171
	v_pk_mul_f32 v[104:105], v[104:105], v[106:107]
	v_pk_mul_f32 v[102:103], v[102:103], v[112:113]
	v_pk_mul_f32 v[106:107], v[100:101], v[108:109]
	v_pk_mul_f32 v[100:101], v[98:99], v[114:115]
	v_lshl_add_u64 v[108:109], s[6:7], 0, v[110:111]
	v_cvt_pk_bf16_f32 v98, v102, v103
	v_cvt_pk_bf16_f32 v99, v104, v105
	v_cvt_pk_bf16_f32 v100, v100, v101
	v_cvt_pk_bf16_f32 v101, v106, v107
	global_store_dwordx4 v[108:109], v[98:101], off sc1
	s_nop 1
	v_add_u32_e32 v98, 0x8000, v0
	v_mov_b32_e32 v99, v1
	v_lshlrev_b64 v[102:103], 1, v[98:99]
	s_waitcnt vmcnt(15)
	v_lshlrev_b32_e32 v104, 16, v172
	v_and_b32_e32 v105, 0xffff0000, v172
	v_lshlrev_b32_e32 v98, 16, v173
	v_and_b32_e32 v99, 0xffff0000, v173
	v_lshlrev_b32_e32 v106, 16, v174
	v_and_b32_e32 v107, 0xffff0000, v174
	v_lshlrev_b32_e32 v100, 16, v175
	v_and_b32_e32 v101, 0xffff0000, v175
	v_pk_mul_f32 v[96:97], v[96:97], v[98:99]
	v_pk_mul_f32 v[94:95], v[94:95], v[104:105]
	v_pk_mul_f32 v[98:99], v[92:93], v[100:101]
	v_pk_mul_f32 v[92:93], v[90:91], v[106:107]
	v_lshl_add_u64 v[100:101], s[6:7], 0, v[102:103]
	v_cvt_pk_bf16_f32 v90, v94, v95
	v_cvt_pk_bf16_f32 v91, v96, v97
	v_cvt_pk_bf16_f32 v92, v92, v93
	v_cvt_pk_bf16_f32 v93, v98, v99
	global_store_dwordx4 v[100:101], v[90:93], off sc1
	s_nop 1
	v_add_u32_e32 v90, 0x8080, v0
	v_mov_b32_e32 v91, v1
	v_lshlrev_b64 v[94:95], 1, v[90:91]
	s_waitcnt vmcnt(15)
	v_lshlrev_b32_e32 v96, 16, v176
	v_and_b32_e32 v97, 0xffff0000, v176
	v_lshlrev_b32_e32 v90, 16, v177
	v_and_b32_e32 v91, 0xffff0000, v177
	v_lshlrev_b32_e32 v98, 16, v178
	v_and_b32_e32 v99, 0xffff0000, v178
	v_lshlrev_b32_e32 v92, 16, v179
	v_and_b32_e32 v93, 0xffff0000, v179
	v_pk_mul_f32 v[88:89], v[88:89], v[90:91]
	v_pk_mul_f32 v[86:87], v[86:87], v[96:97]
	v_pk_mul_f32 v[90:91], v[84:85], v[92:93]
	v_pk_mul_f32 v[84:85], v[82:83], v[98:99]
	v_lshl_add_u64 v[92:93], s[6:7], 0, v[94:95]
	v_cvt_pk_bf16_f32 v82, v86, v87
	v_cvt_pk_bf16_f32 v83, v88, v89
	v_cvt_pk_bf16_f32 v84, v84, v85
	v_cvt_pk_bf16_f32 v85, v90, v91
	global_store_dwordx4 v[92:93], v[82:85], off sc1
	s_nop 1
	v_add_u32_e32 v82, 0xc000, v0
	v_mov_b32_e32 v83, v1
	v_lshlrev_b64 v[86:87], 1, v[82:83]
	s_waitcnt vmcnt(15)
	v_lshlrev_b32_e32 v88, 16, v180
	v_and_b32_e32 v89, 0xffff0000, v180
	v_lshlrev_b32_e32 v82, 16, v181
	v_and_b32_e32 v83, 0xffff0000, v181
	v_lshlrev_b32_e32 v90, 16, v182
	v_and_b32_e32 v91, 0xffff0000, v182
	v_lshlrev_b32_e32 v84, 16, v183
	v_and_b32_e32 v85, 0xffff0000, v183
	v_pk_mul_f32 v[80:81], v[80:81], v[82:83]
	v_pk_mul_f32 v[78:79], v[78:79], v[88:89]
	v_pk_mul_f32 v[82:83], v[76:77], v[84:85]
	v_pk_mul_f32 v[76:77], v[74:75], v[90:91]
	v_lshl_add_u64 v[84:85], s[6:7], 0, v[86:87]
	v_cvt_pk_bf16_f32 v74, v78, v79
	v_cvt_pk_bf16_f32 v75, v80, v81
	v_cvt_pk_bf16_f32 v76, v76, v77
	v_cvt_pk_bf16_f32 v77, v82, v83
	global_store_dwordx4 v[84:85], v[74:77], off sc1
	s_nop 1
	v_add_u32_e32 v74, 0xc080, v0
	v_mov_b32_e32 v75, v1
	v_lshlrev_b64 v[78:79], 1, v[74:75]
	s_waitcnt vmcnt(15)
	v_lshlrev_b32_e32 v80, 16, v184
	v_and_b32_e32 v81, 0xffff0000, v184
	v_lshlrev_b32_e32 v74, 16, v185
	v_and_b32_e32 v75, 0xffff0000, v185
	v_lshlrev_b32_e32 v82, 16, v186
	v_and_b32_e32 v83, 0xffff0000, v186
	v_lshlrev_b32_e32 v76, 16, v187
	v_and_b32_e32 v77, 0xffff0000, v187
	v_pk_mul_f32 v[72:73], v[72:73], v[74:75]
	v_pk_mul_f32 v[70:71], v[70:71], v[80:81]
	v_pk_mul_f32 v[74:75], v[68:69], v[76:77]
	v_pk_mul_f32 v[68:69], v[66:67], v[82:83]
	v_lshl_add_u64 v[76:77], s[6:7], 0, v[78:79]
	v_cvt_pk_bf16_f32 v66, v70, v71
	v_cvt_pk_bf16_f32 v67, v72, v73
	v_cvt_pk_bf16_f32 v68, v68, v69
	v_cvt_pk_bf16_f32 v69, v74, v75
	global_store_dwordx4 v[76:77], v[66:69], off sc1
	s_nop 1
	v_add_u32_e32 v66, 0x20000, v0
	v_mov_b32_e32 v67, v1
	v_lshlrev_b64 v[70:71], 1, v[66:67]
	s_waitcnt vmcnt(15)
	v_lshlrev_b32_e32 v72, 16, v188
	v_and_b32_e32 v73, 0xffff0000, v188
	v_lshlrev_b32_e32 v66, 16, v189
	v_and_b32_e32 v67, 0xffff0000, v189
	v_lshlrev_b32_e32 v74, 16, v190
	v_and_b32_e32 v75, 0xffff0000, v190
	v_lshlrev_b32_e32 v68, 16, v191
	v_and_b32_e32 v69, 0xffff0000, v191
	v_pk_mul_f32 v[64:65], v[64:65], v[66:67]
	v_pk_mul_f32 v[62:63], v[62:63], v[72:73]
	v_pk_mul_f32 v[66:67], v[60:61], v[68:69]
	v_pk_mul_f32 v[60:61], v[58:59], v[74:75]
	v_lshl_add_u64 v[68:69], s[6:7], 0, v[70:71]
	v_cvt_pk_bf16_f32 v58, v62, v63
	v_cvt_pk_bf16_f32 v59, v64, v65
	v_cvt_pk_bf16_f32 v60, v60, v61
	v_cvt_pk_bf16_f32 v61, v66, v67
	global_store_dwordx4 v[68:69], v[58:61], off sc1
	s_nop 1
	v_add_u32_e32 v58, 0x20080, v0
	v_mov_b32_e32 v59, v1
	v_lshlrev_b64 v[62:63], 1, v[58:59]
	s_waitcnt vmcnt(15)
; #define PG8_BAR __builtin_amdgcn_s_barrier()
; #define PG8_SCHED __builtin_amdgcn_sched_barrier(0)
; __device__ __forceinline__ void st8(bf16_t* p, f32x4 a, f32x4 b) { u32x4 w; w.x = pk2(a[0], a[1]); w.y = pk2(a[2], a[3]); w.z = pk2(b[0], b[1]); w.w = pk2(b[2], b[3]); *(u32x4*)p = w; }
; __device__ __forceinline__ void ld8(const bf16_t* p, f32x4& a, f32x4& b) { const u32x4 w = *(const u32x4*)p; a[0] = bflo(w.x); a[1] = bfhi(w.x); a[2] = bflo(w.y); a[3] = bfhi(w.y); b[0] = bflo(w.z); b[1] = bfhi(w.z); b[2] = bflo(w.w); b[3] = bfhi(w.w); }
; template <class Epi, class Sched, bool ALIGN_EPI = false, bool SP2 = false>
; __device__ __forceinline__ void gemm_phase(PG8_LAS unsigned char* lds, const Gemm g, const Sched& S, const Epi& E) {
;     ...
;         if constexpr (ALIGN_EPI) { if (wr == 0) PG8_BAR; }
;         if constexpr (!Epi::AFTER_DRAIN) { PG8_SCHED; int fr_l = fr, fq_l = fq; asm volatile("" : "+v"(fr_l), "+v"(fq_l) :: "memory"); E(acc, cur, wr, wc, fr_l, fq_l); asm volatile("" ::: "memory"); PG8_SCHED; S.done(cur); }
;         if (!has_next) break;
; #pragma unroll
;         for (int a = 0; a < 2; ++a)
; #pragma unroll
;             for (int b = 0; b < 2; ++b)
; #pragma unroll
;                 for (int m = 0; m < 4; ++m)
; #pragma unroll
;                     for (int n = 0; n < 2; ++n) acc[a][b][m][n] = (f32x4){0.f, 0.f, 0.f, 0.f};
;         cur = nxt; cA = nA; cB = nB; ++ui;
;         if constexpr (ALIGN_EPI) { if (wr == 1) PG8_BAR; }
;     }
;     __device__ __forceinline__ void operator()(ACC_T, const pg8::Unit& u, int wr, int wc, int fr, int fq) const {
;         const int row0 = u.pm * 256 + wr * 64 + fr, col0 = u.pn * 256 + wc * 32 + 8 * fq;
; #pragma unroll
;         for (int ai = 0; ai < 2; ++ai)
; #pragma unroll
;             for (int m = 0; m < 4; ++m) { const int row = row0 + ai * 128 + m * 16;
; #pragma unroll
;                 for (int bj = 0; bj < 2; ++bj) { const unsigned off = (unsigned)row * 1024u + col0 + bj * 128; f32x4 g0, g1; ld8(G + off, g0, g1);
;                     f32x4 v0 = acc[ai][bj][m][0] * g0, v1 = acc[ai][bj][m][1] * g1;
;                     if (MODE == 1) { f32x4 p0, p1; ld8(P + off, p0, p1); v0 += p0; v1 += p1; }
;                     st8(O + off, v0, v1); }
;                 asm volatile("" ::: "memory"); }
;     }
	v_lshlrev_b32_e32 v64, 16, v192
	v_and_b32_e32 v65, 0xffff0000, v192
	v_lshlrev_b32_e32 v58, 16, v193
	v_and_b32_e32 v59, 0xffff0000, v193
	v_lshlrev_b32_e32 v66, 16, v194
	v_and_b32_e32 v67, 0xffff0000, v194
	v_lshlrev_b32_e32 v60, 16, v195
	v_and_b32_e32 v61, 0xffff0000, v195
	v_pk_mul_f32 v[56:57], v[56:57], v[58:59]
	v_pk_mul_f32 v[54:55], v[54:55], v[64:65]
	v_pk_mul_f32 v[58:59], v[52:53], v[60:61]
	v_pk_mul_f32 v[52:53], v[50:51], v[66:67]
	v_lshl_add_u64 v[60:61], s[6:7], 0, v[62:63]
	v_cvt_pk_bf16_f32 v50, v54, v55
	v_cvt_pk_bf16_f32 v51, v56, v57
	v_cvt_pk_bf16_f32 v52, v52, v53
	v_cvt_pk_bf16_f32 v53, v58, v59
	global_store_dwordx4 v[60:61], v[50:53], off sc1
	s_nop 1
	v_add_u32_e32 v50, 0x24000, v0
	v_mov_b32_e32 v51, v1
	v_lshlrev_b64 v[54:55], 1, v[50:51]
	s_waitcnt vmcnt(15)
	v_lshlrev_b32_e32 v56, 16, v196
	v_and_b32_e32 v57, 0xffff0000, v196
	v_lshlrev_b32_e32 v50, 16, v197
	v_and_b32_e32 v51, 0xffff0000, v197
	v_lshlrev_b32_e32 v58, 16, v198
	v_and_b32_e32 v59, 0xffff0000, v198
	v_lshlrev_b32_e32 v52, 16, v199
	v_and_b32_e32 v53, 0xffff0000, v199
	v_pk_mul_f32 v[48:49], v[48:49], v[50:51]
	v_pk_mul_f32 v[46:47], v[46:47], v[56:57]
	v_pk_mul_f32 v[50:51], v[44:45], v[52:53]
	v_pk_mul_f32 v[44:45], v[42:43], v[58:59]
	v_lshl_add_u64 v[52:53], s[6:7], 0, v[54:55]
	v_cvt_pk_bf16_f32 v42, v46, v47
	v_cvt_pk_bf16_f32 v43, v48, v49
	v_cvt_pk_bf16_f32 v44, v44, v45
	v_cvt_pk_bf16_f32 v45, v50, v51
	global_store_dwordx4 v[52:53], v[42:45], off sc1
	s_nop 1
	v_add_u32_e32 v42, 0x24080, v0
	v_mov_b32_e32 v43, v1
	v_lshlrev_b64 v[46:47], 1, v[42:43]
	s_waitcnt vmcnt(15)
	v_lshlrev_b32_e32 v48, 16, v200
	v_and_b32_e32 v49, 0xffff0000, v200
	v_lshlrev_b32_e32 v42, 16, v201
	v_and_b32_e32 v43, 0xffff0000, v201
	v_lshlrev_b32_e32 v50, 16, v202
	v_and_b32_e32 v51, 0xffff0000, v202
	v_lshlrev_b32_e32 v44, 16, v203
	v_and_b32_e32 v45, 0xffff0000, v203
	v_pk_mul_f32 v[40:41], v[40:41], v[42:43]
	v_pk_mul_f32 v[38:39], v[38:39], v[48:49]
	v_pk_mul_f32 v[42:43], v[36:37], v[44:45]
	v_pk_mul_f32 v[36:37], v[34:35], v[50:51]
	v_lshl_add_u64 v[44:45], s[6:7], 0, v[46:47]
	v_cvt_pk_bf16_f32 v34, v38, v39
	v_cvt_pk_bf16_f32 v35, v40, v41
	v_cvt_pk_bf16_f32 v36, v36, v37
	v_cvt_pk_bf16_f32 v37, v42, v43
	global_store_dwordx4 v[44:45], v[34:37], off sc1
	s_nop 1
	v_add_u32_e32 v34, 0x28000, v0
	v_mov_b32_e32 v35, v1
	v_lshlrev_b64 v[38:39], 1, v[34:35]
	s_waitcnt vmcnt(15)
	v_lshlrev_b32_e32 v40, 16, v204
	v_and_b32_e32 v41, 0xffff0000, v204
	v_lshlrev_b32_e32 v34, 16, v205
	v_and_b32_e32 v35, 0xffff0000, v205
	v_lshlrev_b32_e32 v42, 16, v206
	v_and_b32_e32 v43, 0xffff0000, v206
	v_lshlrev_b32_e32 v36, 16, v207
	v_and_b32_e32 v37, 0xffff0000, v207
	v_pk_mul_f32 v[32:33], v[32:33], v[34:35]
	v_pk_mul_f32 v[30:31], v[30:31], v[40:41]
	v_pk_mul_f32 v[34:35], v[28:29], v[36:37]
	v_pk_mul_f32 v[28:29], v[26:27], v[42:43]
	v_lshl_add_u64 v[36:37], s[6:7], 0, v[38:39]
	v_cvt_pk_bf16_f32 v26, v30, v31
	v_cvt_pk_bf16_f32 v27, v32, v33
	v_cvt_pk_bf16_f32 v28, v28, v29
	v_cvt_pk_bf16_f32 v29, v34, v35
	global_store_dwordx4 v[36:37], v[26:29], off sc1
	s_nop 1
	v_add_u32_e32 v26, 0x28080, v0
	v_mov_b32_e32 v27, v1
	v_lshlrev_b64 v[30:31], 1, v[26:27]
	s_waitcnt vmcnt(15)
	v_lshlrev_b32_e32 v32, 16, v208
	v_and_b32_e32 v33, 0xffff0000, v208
	v_lshlrev_b32_e32 v26, 16, v209
	v_and_b32_e32 v27, 0xffff0000, v209
	v_lshlrev_b32_e32 v34, 16, v210
	v_and_b32_e32 v35, 0xffff0000, v210
	v_lshlrev_b32_e32 v28, 16, v211
	v_and_b32_e32 v29, 0xffff0000, v211
	v_pk_mul_f32 v[24:25], v[24:25], v[26:27]
	v_pk_mul_f32 v[22:23], v[22:23], v[32:33]
	v_pk_mul_f32 v[26:27], v[20:21], v[28:29]
	v_pk_mul_f32 v[20:21], v[18:19], v[34:35]
	v_lshl_add_u64 v[28:29], s[6:7], 0, v[30:31]
	v_cvt_pk_bf16_f32 v18, v22, v23
	v_cvt_pk_bf16_f32 v19, v24, v25
	v_cvt_pk_bf16_f32 v20, v20, v21
	v_cvt_pk_bf16_f32 v21, v26, v27
	global_store_dwordx4 v[28:29], v[18:21], off sc1
	s_nop 1
	v_add_u32_e32 v18, 0x2c000, v0
	v_mov_b32_e32 v19, v1
	v_lshlrev_b64 v[22:23], 1, v[18:19]
	v_add_u32_e32 v0, 0x2c080, v0
	s_waitcnt vmcnt(15)
	v_lshlrev_b32_e32 v24, 16, v212
	v_and_b32_e32 v25, 0xffff0000, v212
	v_lshlrev_b32_e32 v18, 16, v213
	v_and_b32_e32 v19, 0xffff0000, v213
	v_lshlrev_b32_e32 v26, 16, v214
	v_and_b32_e32 v27, 0xffff0000, v214
	v_lshlrev_b32_e32 v20, 16, v215
	v_and_b32_e32 v21, 0xffff0000, v215
	v_pk_mul_f32 v[16:17], v[16:17], v[18:19]
	v_pk_mul_f32 v[14:15], v[14:15], v[24:25]
	v_pk_mul_f32 v[18:19], v[12:13], v[20:21]
	v_pk_mul_f32 v[12:13], v[10:11], v[26:27]
	v_lshl_add_u64 v[20:21], s[6:7], 0, v[22:23]
	v_cvt_pk_bf16_f32 v10, v14, v15
	v_cvt_pk_bf16_f32 v11, v16, v17
	v_cvt_pk_bf16_f32 v12, v12, v13
	v_cvt_pk_bf16_f32 v13, v18, v19
	v_lshlrev_b64 v[14:15], 1, v[0:1]
	global_store_dwordx4 v[20:21], v[10:13], off sc1
	s_nop 1
	s_waitcnt vmcnt(15)
	v_lshlrev_b32_e32 v16, 16, v216
	v_and_b32_e32 v17, 0xffff0000, v216
	v_lshlrev_b32_e32 v10, 16, v217
	v_and_b32_e32 v11, 0xffff0000, v217
	v_lshlrev_b32_e32 v18, 16, v218
	v_and_b32_e32 v19, 0xffff0000, v218
	v_lshlrev_b32_e32 v12, 16, v219
	v_and_b32_e32 v13, 0xffff0000, v219
	v_pk_mul_f32 v[8:9], v[8:9], v[10:11]
	v_pk_mul_f32 v[6:7], v[6:7], v[16:17]
	v_pk_mul_f32 v[10:11], v[4:5], v[12:13]
	v_pk_mul_f32 v[4:5], v[2:3], v[18:19]
	v_lshl_add_u64 v[12:13], s[6:7], 0, v[14:15]
	v_cvt_pk_bf16_f32 v2, v6, v7
	v_cvt_pk_bf16_f32 v3, v8, v9
	v_cvt_pk_bf16_f32 v4, v4, v5
	v_cvt_pk_bf16_f32 v5, v10, v11
	global_store_dwordx4 v[12:13], v[2:5], off sc1
	s_andn2_b64 vcc, exec, s[38:39]
	s_mov_b64 s[8:9], -1
	s_cbranch_vccnz .LBB0_1030
	s_andn2_b64 vcc, exec, s[4:5]
	s_cbranch_vccnz .LBB0_1029
	s_barrier
	s_branch .LBB0_1029
